# V-GEMM epilogue: ss loads of each column half issued together (2 waits instead of 8)
# baseline (speedup 1.0000x reference)
; #define G_STAGE(bufoff, gbase, voff) do { _Pragma("unroll") for (int _i = 0; _i < 2; ++_i) { unsigned _vo = (voff)[_i]; asm volatile("" : "+v"(_vo));   \
;     __builtin_amdgcn_global_load_lds((const unsigned*)((const char*)(gbase) + _vo), (LAS unsigned*)(lds + (bufoff) + ldsw + _i * 8192), 16, 0, 0); } } while (0)
; #define G_LDA(dst, b, h) do { _Pragma("unroll") for (int m = 0; m < 4; ++m) _Pragma("unroll") for (int k = 0; k < 2; ++k) dst[m][k] = *(const LAS bf16x8*)(lds + G_SA(b, h) + aoff + m * 2048 + k * 1024); } while (0)
; #define G_LDB(dst, b, h) do { _Pragma("unroll") for (int n = 0; n < 2; ++n) _Pragma("unroll") for (int k = 0; k < 2; ++k) dst[n][k] = *(const LAS bf16x8*)(lds + G_SB(b, h) + boff + n * 2048 + k * 1024); } while (0)
; #define G_MMA(ai, bj, At, Bt) do { __builtin_amdgcn_s_setprio(1); _Pragma("unroll") for (int m = 0; m < 4; ++m) _Pragma("unroll") for (int n = 0; n < 2; ++n) _Pragma("unroll") for (int k = 0; k < 2; ++k) \
;     acc[ai][bj][m][n] = __builtin_amdgcn_mfma_f32_16x16x32_bf16(Bt[n][k], At[m][k], acc[ai][bj][m][n], 0, 0, 0); __builtin_amdgcn_s_setprio(0); } while (0)
; #define G_WAIT_V(n) asm volatile("s_waitcnt vmcnt(" #n ")" ::: "memory")
; #define G_WAIT_L(n) asm volatile("s_waitcnt lgkmcnt(" #n ")" ::: "memory")
; #define G_BAR __builtin_amdgcn_s_barrier()
; #define G_SCHED __builtin_amdgcn_sched_barrier(0)
; template <class Epi>
; __device__ __forceinline__ void gemm_phase(LAS unsigned char* lds, const int K, const unsigned lda_b, const unsigned ldb_b, const Map& M, const Epi& E) {
;     ...
;       G_LDB(B0, 0, 0); G_SCHED; G_LDA(At, 0, 0); G_STAGE(G_SA(1, 1), a1h1, voffA);
;       G_WAIT_L(8); G_BAR; G_WAIT_L(0); G_MMA(0, 0, At, B0); G_BAR; G_SCHED;
;       G_LDB(B1, 0, 1); G_STAGE(G_SB(0, 0), b2h0, voffB);
;       G_BAR; G_WAIT_L(0); G_MMA(0, 1, At, B1); G_BAR;
;       G_LDA(At, 0, 1); G_STAGE(G_SA(0, 0), a2h0, voffA);
;       G_BAR; G_WAIT_L(0); G_MMA(1, 0, At, B0); G_BAR; G_SCHED;
;       G_STAGE(G_SB(0, 1), b2h1, voffB);
;       G_WAIT_V(6); G_BAR; G_MMA(1, 1, At, B1); G_BAR;
.LBB0_651:
	s_add_u32 s22, s2, 0xfff80080
	s_addc_u32 s34, s3, -1
	s_add_u32 s35, s29, s46
	s_addc_u32 s38, s30, 0
	s_add_i32 vcc_lo, 0, 0x10000
	v_add_u32_e32 v80, vcc_lo, v158
	ds_read_b128 v[132:135], v80
	ds_read_b128 v[136:139], v80 offset:1024
	ds_read_b128 v[140:143], v80 offset:2048
	ds_read_b128 v[144:147], v80 offset:3072
	s_cmp_eq_u32 s31, 28
	s_cselect_b32 s43, s9, s34
	s_cselect_b32 s42, s8, s22
	s_cselect_b32 s45, s37, s30
	s_cselect_b32 s44, s36, s29
	v_mov_b32_e32 v80, v153
	s_cselect_b32 s39, s28, s38
	s_cselect_b32 s38, s0, s35
	s_add_u32 s68, s42, 0x80000
	ds_read_b128 v[148:151], v170
	ds_read_b128 v[172:175], v170 offset:1024
	ds_read_b128 v[190:193], v170 offset:2048
	ds_read_b128 v[194:197], v170 offset:3072
	ds_read_b128 v[198:201], v170 offset:4096
	ds_read_b128 v[202:205], v170 offset:5120
	ds_read_b128 v[206:209], v170 offset:6144
	ds_read_b128 v[210:213], v170 offset:7168
	s_addc_u32 s69, s43, 0
	s_add_i32 m0, s48, 0xc000
	s_nop 0
	global_load_lds_dwordx4 v80, s[2:3]
	v_mov_b32_e32 v80, v155
	s_add_i32 m0, s48, 0xe000
	s_nop 0
	global_load_lds_dwordx4 v80, s[2:3]
	s_waitcnt lgkmcnt(8)
	s_barrier
	s_waitcnt lgkmcnt(0)
	s_setprio 1
	s_waitcnt lgkmcnt(0)
	v_mfma_f32_16x16x32_bf16 v[126:129], v[132:135], v[148:151], v[126:129]
	v_mfma_f32_16x16x32_bf16 v[122:125], v[140:143], v[148:151], v[122:125]
	v_mfma_f32_16x16x32_bf16 v[110:113], v[132:135], v[190:193], v[110:113]
	v_mfma_f32_16x16x32_bf16 v[106:109], v[140:143], v[190:193], v[106:109]
	v_mfma_f32_16x16x32_bf16 v[94:97], v[132:135], v[198:201], v[94:97]
	v_mfma_f32_16x16x32_bf16 v[90:93], v[140:143], v[198:201], v[90:93]
	v_mfma_f32_16x16x32_bf16 v[76:79], v[132:135], v[206:209], v[76:79]
	v_mfma_f32_16x16x32_bf16 v[72:75], v[140:143], v[206:209], v[72:75]
	v_mfma_f32_16x16x32_bf16 v[126:129], v[136:139], v[172:175], v[126:129]
	v_mfma_f32_16x16x32_bf16 v[122:125], v[144:147], v[172:175], v[122:125]
	v_mfma_f32_16x16x32_bf16 v[110:113], v[136:139], v[194:197], v[110:113]
	v_mfma_f32_16x16x32_bf16 v[106:109], v[144:147], v[194:197], v[106:109]
	v_mfma_f32_16x16x32_bf16 v[94:97], v[136:139], v[202:205], v[94:97]
	v_mfma_f32_16x16x32_bf16 v[90:93], v[144:147], v[202:205], v[90:93]
	v_mfma_f32_16x16x32_bf16 v[76:79], v[136:139], v[210:213], v[76:79]
	v_mfma_f32_16x16x32_bf16 v[72:75], v[144:147], v[210:213], v[72:75]
	s_setprio 0
	s_barrier
	s_add_i32 s22, 0, 0x14000
	v_add_u32_e32 v80, s22, v158
	ds_read_b128 v[214:217], v80
	ds_read_b128 v[226:229], v80 offset:1024
	ds_read_b128 v[238:241], v80 offset:2048
	ds_read_b128 v[242:245], v80 offset:3072
	v_mov_b32_e32 v80, v154
	s_add_i32 s34, vcc_lo, s47
	s_mov_b32 m0, s34
	s_nop 0
	global_load_lds_dwordx4 v80, s[44:45]
	v_mov_b32_e32 v80, v156
	s_add_i32 m0, s34, 0x2000
	s_nop 0
	global_load_lds_dwordx4 v80, s[44:45]
	s_barrier
	s_waitcnt lgkmcnt(0)
	s_setprio 1
	s_waitcnt lgkmcnt(0)
	v_mfma_f32_16x16x32_bf16 v[118:121], v[214:217], v[148:151], v[118:121]
	v_mfma_f32_16x16x32_bf16 v[114:117], v[238:241], v[148:151], v[114:117]
	v_mfma_f32_16x16x32_bf16 v[102:105], v[214:217], v[190:193], v[102:105]
	v_mfma_f32_16x16x32_bf16 v[98:101], v[238:241], v[190:193], v[98:101]
	v_mfma_f32_16x16x32_bf16 v[86:89], v[214:217], v[198:201], v[86:89]
	v_mfma_f32_16x16x32_bf16 v[82:85], v[238:241], v[198:201], v[82:85]
	v_mfma_f32_16x16x32_bf16 v[68:71], v[214:217], v[206:209], v[68:71]
	v_mfma_f32_16x16x32_bf16 v[64:67], v[238:241], v[206:209], v[64:67]
	v_mfma_f32_16x16x32_bf16 v[118:121], v[226:229], v[172:175], v[118:121]
	v_mfma_f32_16x16x32_bf16 v[114:117], v[242:245], v[172:175], v[114:117]
	v_mfma_f32_16x16x32_bf16 v[102:105], v[226:229], v[194:197], v[102:105]
	v_mfma_f32_16x16x32_bf16 v[98:101], v[242:245], v[194:197], v[98:101]
	v_mfma_f32_16x16x32_bf16 v[86:89], v[226:229], v[202:205], v[86:89]
	v_mfma_f32_16x16x32_bf16 v[82:85], v[242:245], v[202:205], v[82:85]
	v_mfma_f32_16x16x32_bf16 v[68:71], v[226:229], v[210:213], v[68:71]
	v_mfma_f32_16x16x32_bf16 v[64:67], v[242:245], v[210:213], v[64:67]
	s_setprio 0
	v_mov_b32_e32 v80, v153
	s_mov_b32 m0, s48
	s_barrier
	ds_read_b128 v[148:151], v170 offset:16384
	ds_read_b128 v[172:175], v170 offset:17408
	ds_read_b128 v[190:193], v170 offset:18432
	ds_read_b128 v[194:197], v170 offset:19456
	ds_read_b128 v[198:201], v170 offset:20480
	ds_read_b128 v[202:205], v170 offset:21504
	ds_read_b128 v[206:209], v170 offset:22528
	ds_read_b128 v[210:213], v170 offset:23552
	s_nop 0
	global_load_lds_dwordx4 v80, s[42:43]
	v_mov_b32_e32 v80, v155
	s_mov_b32 m0, s49
	s_nop 0
	global_load_lds_dwordx4 v80, s[42:43]
	s_barrier
	s_waitcnt lgkmcnt(0)
	s_setprio 1
	s_waitcnt lgkmcnt(0)
	v_mfma_f32_16x16x32_bf16 v[60:63], v[132:135], v[148:151], v[60:63]
	v_mfma_f32_16x16x32_bf16 v[56:59], v[140:143], v[148:151], v[56:59]
	v_mfma_f32_16x16x32_bf16 v[44:47], v[132:135], v[190:193], v[44:47]
	v_mfma_f32_16x16x32_bf16 v[40:43], v[140:143], v[190:193], v[40:43]
	v_mfma_f32_16x16x32_bf16 v[28:31], v[132:135], v[198:201], v[28:31]
	v_mfma_f32_16x16x32_bf16 v[24:27], v[140:143], v[198:201], v[24:27]
	v_mfma_f32_16x16x32_bf16 v[12:15], v[132:135], v[206:209], v[12:15]
	v_mfma_f32_16x16x32_bf16 v[8:11], v[140:143], v[206:209], v[8:11]
	v_mfma_f32_16x16x32_bf16 v[60:63], v[136:139], v[172:175], v[60:63]
	v_mfma_f32_16x16x32_bf16 v[56:59], v[144:147], v[172:175], v[56:59]
	v_mfma_f32_16x16x32_bf16 v[44:47], v[136:139], v[194:197], v[44:47]
	v_mfma_f32_16x16x32_bf16 v[40:43], v[144:147], v[194:197], v[40:43]
	v_mfma_f32_16x16x32_bf16 v[28:31], v[136:139], v[202:205], v[28:31]
	v_mfma_f32_16x16x32_bf16 v[24:27], v[144:147], v[202:205], v[24:27]
	v_mfma_f32_16x16x32_bf16 v[12:15], v[136:139], v[210:213], v[12:15]
	v_mfma_f32_16x16x32_bf16 v[8:11], v[144:147], v[210:213], v[8:11]
	s_setprio 0
	s_barrier
; #define G_STAGE(bufoff, gbase, voff) do { _Pragma("unroll") for (int _i = 0; _i < 2; ++_i) { unsigned _vo = (voff)[_i]; asm volatile("" : "+v"(_vo));   \
;     __builtin_amdgcn_global_load_lds((const unsigned*)((const char*)(gbase) + _vo), (LAS unsigned*)(lds + (bufoff) + ldsw + _i * 8192), 16, 0, 0); } } while (0)
; #define G_LDA(dst, b, h) do { _Pragma("unroll") for (int m = 0; m < 4; ++m) _Pragma("unroll") for (int k = 0; k < 2; ++k) dst[m][k] = *(const LAS bf16x8*)(lds + G_SA(b, h) + aoff + m * 2048 + k * 1024); } while (0)
; #define G_LDB(dst, b, h) do { _Pragma("unroll") for (int n = 0; n < 2; ++n) _Pragma("unroll") for (int k = 0; k < 2; ++k) dst[n][k] = *(const LAS bf16x8*)(lds + G_SB(b, h) + boff + n * 2048 + k * 1024); } while (0)
; #define G_MMA(ai, bj, At, Bt) do { __builtin_amdgcn_s_setprio(1); _Pragma("unroll") for (int m = 0; m < 4; ++m) _Pragma("unroll") for (int n = 0; n < 2; ++n) _Pragma("unroll") for (int k = 0; k < 2; ++k) \
;     acc[ai][bj][m][n] = __builtin_amdgcn_mfma_f32_16x16x32_bf16(Bt[n][k], At[m][k], acc[ai][bj][m][n], 0, 0, 0); __builtin_amdgcn_s_setprio(0); } while (0)
; #define G_WAIT_L(n) asm volatile("s_waitcnt lgkmcnt(" #n ")" ::: "memory")
; #define G_BAR __builtin_amdgcn_s_barrier()
; #define G_SCHED __builtin_amdgcn_sched_barrier(0)
; template <class Epi>
; __device__ __forceinline__ void gemm_phase(LAS unsigned char* lds, const int K, const unsigned lda_b, const unsigned ldb_b, const Map& M, const Epi& E) {
;     ...
;       G_LDB(B0, 1, 0); G_SCHED; G_LDA(At, 1, 0); G_STAGE(G_SA(0, 1), a2h1, voffA);
;       G_WAIT_L(8); G_BAR; G_WAIT_L(0); G_MMA(0, 0, At, B0); G_BAR; G_SCHED;
;       G_LDB(B1, 1, 1); G_STAGE(G_SB(1, 0), b2h0 + kstep, voffB);
;       G_BAR; G_WAIT_L(0); G_MMA(0, 1, At, B1); G_BAR;
;       G_LDA(At, 1, 1); G_STAGE(G_SA(1, 0), a2h0 + kstep, voffA);
;       G_BAR; G_WAIT_L(0); G_MMA(1, 0, At, B0); G_BAR; G_SCHED;
	v_mov_b32_e32 v80, v154
	s_add_i32 s22, s22, s47
	s_mov_b32 m0, s22
	s_nop 0
	global_load_lds_dwordx4 v80, s[38:39]
	v_mov_b32_e32 v80, v156
	s_add_i32 m0, s22, 0x2000
	s_nop 0
	global_load_lds_dwordx4 v80, s[38:39]
	s_waitcnt vmcnt(6)
	s_barrier
	s_setprio 1
	v_mfma_f32_16x16x32_bf16 v[52:55], v[214:217], v[148:151], v[52:55]
	v_mfma_f32_16x16x32_bf16 v[48:51], v[238:241], v[148:151], v[48:51]
	v_mfma_f32_16x16x32_bf16 v[36:39], v[214:217], v[190:193], v[36:39]
	v_mfma_f32_16x16x32_bf16 v[32:35], v[238:241], v[190:193], v[32:35]
	v_mfma_f32_16x16x32_bf16 v[20:23], v[214:217], v[198:201], v[20:23]
	v_mfma_f32_16x16x32_bf16 v[16:19], v[238:241], v[198:201], v[16:19]
	v_mfma_f32_16x16x32_bf16 v[4:7], v[214:217], v[206:209], v[4:7]
	v_mfma_f32_16x16x32_bf16 v[0:3], v[238:241], v[206:209], v[0:3]
	v_mfma_f32_16x16x32_bf16 v[52:55], v[226:229], v[172:175], v[52:55]
	v_mfma_f32_16x16x32_bf16 v[48:51], v[242:245], v[172:175], v[48:51]
	v_mfma_f32_16x16x32_bf16 v[36:39], v[226:229], v[194:197], v[36:39]
	v_mfma_f32_16x16x32_bf16 v[32:35], v[242:245], v[194:197], v[32:35]
	v_mfma_f32_16x16x32_bf16 v[20:23], v[226:229], v[202:205], v[20:23]
	v_mfma_f32_16x16x32_bf16 v[16:19], v[242:245], v[202:205], v[16:19]
	v_mfma_f32_16x16x32_bf16 v[4:7], v[226:229], v[210:213], v[4:7]
	v_mfma_f32_16x16x32_bf16 v[0:3], v[242:245], v[210:213], v[0:3]
	s_setprio 0
	s_add_i32 s22, 0, 0x18000
	v_add_u32_e32 v80, s22, v158
	s_barrier
	ds_read_b128 v[132:135], v80
	ds_read_b128 v[136:139], v80 offset:1024
	ds_read_b128 v[140:143], v80 offset:2048
	ds_read_b128 v[144:147], v80 offset:3072
	v_mov_b32_e32 v80, v153
	s_mov_b32 m0, s61
	ds_read_b128 v[148:151], v170 offset:32768
	ds_read_b128 v[172:175], v170 offset:33792
	ds_read_b128 v[190:193], v170 offset:34816
	ds_read_b128 v[194:197], v170 offset:35840
	ds_read_b128 v[198:201], v170 offset:36864
	ds_read_b128 v[202:205], v170 offset:37888
	ds_read_b128 v[206:209], v170 offset:38912
	ds_read_b128 v[210:213], v170 offset:39936
	s_nop 0
	global_load_lds_dwordx4 v80, s[68:69]
	v_mov_b32_e32 v80, v155
	s_mov_b32 m0, s66
	s_nop 0
	global_load_lds_dwordx4 v80, s[68:69]
	s_waitcnt lgkmcnt(8)
	s_barrier
	s_waitcnt lgkmcnt(0)
	s_setprio 1
	s_waitcnt lgkmcnt(0)
	v_mfma_f32_16x16x32_bf16 v[126:129], v[132:135], v[148:151], v[126:129]
	v_mfma_f32_16x16x32_bf16 v[122:125], v[140:143], v[148:151], v[122:125]
	v_mfma_f32_16x16x32_bf16 v[110:113], v[132:135], v[190:193], v[110:113]
	v_mfma_f32_16x16x32_bf16 v[106:109], v[140:143], v[190:193], v[106:109]
	v_mfma_f32_16x16x32_bf16 v[94:97], v[132:135], v[198:201], v[94:97]
	v_mfma_f32_16x16x32_bf16 v[90:93], v[140:143], v[198:201], v[90:93]
	v_mfma_f32_16x16x32_bf16 v[76:79], v[132:135], v[206:209], v[76:79]
	v_mfma_f32_16x16x32_bf16 v[72:75], v[140:143], v[206:209], v[72:75]
	v_mfma_f32_16x16x32_bf16 v[126:129], v[136:139], v[172:175], v[126:129]
	v_mfma_f32_16x16x32_bf16 v[122:125], v[144:147], v[172:175], v[122:125]
	v_mfma_f32_16x16x32_bf16 v[110:113], v[136:139], v[194:197], v[110:113]
	v_mfma_f32_16x16x32_bf16 v[106:109], v[144:147], v[194:197], v[106:109]
	v_mfma_f32_16x16x32_bf16 v[94:97], v[136:139], v[202:205], v[94:97]
	v_mfma_f32_16x16x32_bf16 v[90:93], v[144:147], v[202:205], v[90:93]
	v_mfma_f32_16x16x32_bf16 v[76:79], v[136:139], v[210:213], v[76:79]
	v_mfma_f32_16x16x32_bf16 v[72:75], v[144:147], v[210:213], v[72:75]
	s_setprio 0
	s_barrier
	s_add_i32 s34, 0, 0x1c000
	v_add_u32_e32 v80, s34, v158
	ds_read_b128 v[214:217], v80
	ds_read_b128 v[226:229], v80 offset:1024
	ds_read_b128 v[238:241], v80 offset:2048
	ds_read_b128 v[242:245], v80 offset:3072
	v_mov_b32_e32 v80, v154
	s_add_i32 s22, s22, s47
	s_add_i32 m0, s22, 0xffffff80
	v_mov_b32_e32 v80, v156
	global_load_lds_dwordx4 v154, s[44:45] offset:128
	s_add_i32 m0, s22, 0x1f80
	s_nop 0
	global_load_lds_dwordx4 v156, s[44:45] offset:128
	s_barrier
	s_waitcnt lgkmcnt(0)
	s_setprio 1
	s_waitcnt lgkmcnt(0)
	v_mfma_f32_16x16x32_bf16 v[118:121], v[214:217], v[148:151], v[118:121]
	v_mfma_f32_16x16x32_bf16 v[114:117], v[238:241], v[148:151], v[114:117]
	v_mfma_f32_16x16x32_bf16 v[102:105], v[214:217], v[190:193], v[102:105]
	v_mfma_f32_16x16x32_bf16 v[98:101], v[238:241], v[190:193], v[98:101]
	v_mfma_f32_16x16x32_bf16 v[86:89], v[214:217], v[198:201], v[86:89]
	v_mfma_f32_16x16x32_bf16 v[82:85], v[238:241], v[198:201], v[82:85]
	v_mfma_f32_16x16x32_bf16 v[68:71], v[214:217], v[206:209], v[68:71]
	v_mfma_f32_16x16x32_bf16 v[64:67], v[238:241], v[206:209], v[64:67]
	v_mfma_f32_16x16x32_bf16 v[118:121], v[226:229], v[172:175], v[118:121]
	v_mfma_f32_16x16x32_bf16 v[114:117], v[242:245], v[172:175], v[114:117]
	v_mfma_f32_16x16x32_bf16 v[102:105], v[226:229], v[194:197], v[102:105]
	v_mfma_f32_16x16x32_bf16 v[98:101], v[242:245], v[194:197], v[98:101]
	v_mfma_f32_16x16x32_bf16 v[86:89], v[226:229], v[202:205], v[86:89]
	v_mfma_f32_16x16x32_bf16 v[82:85], v[242:245], v[202:205], v[82:85]
	v_mfma_f32_16x16x32_bf16 v[68:71], v[226:229], v[210:213], v[68:71]
	v_mfma_f32_16x16x32_bf16 v[64:67], v[242:245], v[210:213], v[64:67]
	s_setprio 0
	v_mov_b32_e32 v80, v153
	s_barrier
	ds_read_b128 v[148:151], v170 offset:49152
	ds_read_b128 v[172:175], v170 offset:50176
	ds_read_b128 v[190:193], v170 offset:51200
	ds_read_b128 v[194:197], v170 offset:52224
	ds_read_b128 v[198:201], v170 offset:53248
	ds_read_b128 v[202:205], v170 offset:54272
	ds_read_b128 v[206:209], v170 offset:55296
	ds_read_b128 v[210:213], v170 offset:56320
	s_add_i32 m0, s67, 0xffffff80
	v_mov_b32_e32 v80, v155
	global_load_lds_dwordx4 v153, s[42:43] offset:128
	s_add_i32 m0, s76, 0xffffff80
	s_nop 0
	global_load_lds_dwordx4 v155, s[42:43] offset:128
	s_barrier
; __device__ __forceinline__ float rinv_of(unsigned long long ss) { return rsqrtf((float)ss * (1.f / 16777216.f) * (1.f / DM) + 1e-6f); }
;   __device__ __forceinline__ void operator()(const f32x4 (&acc)[2][2][4][2], const Unit& u, const EpiCtx& x_, int wr, int wc, int fr, int fq) const {
;     ...
;     { const int lg = x_.p0, S = x_.p1, L = S >> lg;
; #pragma unroll
;       for (int bj = 0; bj < 2; ++bj) {
;         const int col = u.c0 + wc * 64 + bj * 32 + 8 * fq, seq = col / S, rem = col % S, r = rem / L, m0 = rem % L;
;         const unsigned long long* sp = x_.ss + (size_t)seq * S + r;
; #pragma unroll
;         for (int i = 0; i < 8; ++i) cs[bj][i >> 2][i & 3] = rinv_of(sp[(size_t)(m0 + i) << lg]);
;       } }
	s_waitcnt lgkmcnt(0)
	s_setprio 1
	s_waitcnt lgkmcnt(0)
	v_mfma_f32_16x16x32_bf16 v[60:63], v[132:135], v[148:151], v[60:63]
	v_mfma_f32_16x16x32_bf16 v[56:59], v[140:143], v[148:151], v[56:59]
	v_mfma_f32_16x16x32_bf16 v[44:47], v[132:135], v[190:193], v[44:47]
	v_mfma_f32_16x16x32_bf16 v[40:43], v[140:143], v[190:193], v[40:43]
	v_mfma_f32_16x16x32_bf16 v[28:31], v[132:135], v[198:201], v[28:31]
	v_mfma_f32_16x16x32_bf16 v[24:27], v[140:143], v[198:201], v[24:27]
	v_mfma_f32_16x16x32_bf16 v[12:15], v[132:135], v[206:209], v[12:15]
	v_mfma_f32_16x16x32_bf16 v[8:11], v[140:143], v[206:209], v[8:11]
	v_mfma_f32_16x16x32_bf16 v[60:63], v[136:139], v[172:175], v[60:63]
	v_mfma_f32_16x16x32_bf16 v[56:59], v[144:147], v[172:175], v[56:59]
	v_mfma_f32_16x16x32_bf16 v[44:47], v[136:139], v[194:197], v[44:47]
	v_mfma_f32_16x16x32_bf16 v[40:43], v[144:147], v[194:197], v[40:43]
	v_mfma_f32_16x16x32_bf16 v[28:31], v[136:139], v[202:205], v[28:31]
	v_mfma_f32_16x16x32_bf16 v[24:27], v[144:147], v[202:205], v[24:27]
	v_mfma_f32_16x16x32_bf16 v[12:15], v[136:139], v[210:213], v[12:15]
	v_mfma_f32_16x16x32_bf16 v[8:11], v[144:147], v[210:213], v[8:11]
	s_setprio 0
	s_barrier
	v_mov_b32_e32 v80, v154
	s_add_i32 s22, s34, s47
	s_add_i32 m0, s22, 0xffffff80
	v_mov_b32_e32 v80, v156
	global_load_lds_dwordx4 v154, s[38:39] offset:128
	s_add_i32 m0, s22, 0x1f80
	s_nop 0
	global_load_lds_dwordx4 v156, s[38:39] offset:128
	s_waitcnt vmcnt(6)
	s_barrier
	s_setprio 1
	v_mfma_f32_16x16x32_bf16 v[52:55], v[214:217], v[148:151], v[52:55]
	v_mfma_f32_16x16x32_bf16 v[48:51], v[238:241], v[148:151], v[48:51]
	v_mfma_f32_16x16x32_bf16 v[36:39], v[214:217], v[190:193], v[36:39]
	v_mfma_f32_16x16x32_bf16 v[32:35], v[238:241], v[190:193], v[32:35]
	v_mfma_f32_16x16x32_bf16 v[20:23], v[214:217], v[198:201], v[20:23]
	v_mfma_f32_16x16x32_bf16 v[16:19], v[238:241], v[198:201], v[16:19]
	v_mfma_f32_16x16x32_bf16 v[4:7], v[214:217], v[206:209], v[4:7]
	v_mfma_f32_16x16x32_bf16 v[0:3], v[238:241], v[206:209], v[0:3]
	v_mfma_f32_16x16x32_bf16 v[52:55], v[226:229], v[172:175], v[52:55]
	v_mfma_f32_16x16x32_bf16 v[48:51], v[242:245], v[172:175], v[48:51]
	v_mfma_f32_16x16x32_bf16 v[36:39], v[226:229], v[194:197], v[36:39]
	v_mfma_f32_16x16x32_bf16 v[32:35], v[242:245], v[194:197], v[32:35]
	v_mfma_f32_16x16x32_bf16 v[20:23], v[226:229], v[202:205], v[20:23]
	v_mfma_f32_16x16x32_bf16 v[16:19], v[242:245], v[202:205], v[16:19]
	v_mfma_f32_16x16x32_bf16 v[4:7], v[226:229], v[210:213], v[4:7]
	v_mfma_f32_16x16x32_bf16 v[0:3], v[242:245], v[210:213], v[0:3]
	s_setprio 0
	s_add_i32 s31, s31, 2
	s_add_u32 s29, s29, 0x100
	s_addc_u32 s30, s30, 0
	s_add_u32 s2, s2, 0x100
	s_addc_u32 s3, s3, 0
	s_cmp_gt_u32 s31, 29
	s_barrier
	s_cbranch_scc0 .LBB0_651
	v_add_u32_e32 v171, s97, v159
	v_readfirstlane_b32 s0, v130
	v_sub_u32_e32 v130, 0, v171
	v_max_i32_e32 v130, v171, v130
	v_readfirstlane_b32 s42, v131
	v_mul_hi_u32 v131, v130, v152
	v_mul_lo_u32 v132, v131, s17
	v_sub_u32_e32 v130, v130, v132
	v_cmp_le_u32_e32 vcc, s17, v130
	v_add_u32_e32 v132, 1, v131
	v_ashrrev_i32_e32 v80, 31, v171
	v_cndmask_b32_e32 v131, v131, v132, vcc
	v_subrev_u32_e32 v132, s17, v130
	v_cndmask_b32_e32 v130, v130, v132, vcc
	v_cmp_le_u32_e32 vcc, s17, v130
	v_add_u32_e32 v130, 1, v131
	v_mov_b64_e32 v[136:137], s[62:63]
	v_cndmask_b32_e32 v130, v131, v130, vcc
	v_xor_b32_e32 v130, v130, v80
	v_sub_u32_e32 v130, v130, v80
	v_mul_lo_u32 v80, v130, s17
	v_sub_u32_e32 v80, v171, v80
	v_sub_u32_e32 v132, 0, v80
	v_max_i32_e32 v132, v80, v132
	v_mul_hi_u32 v133, v132, v169
	v_mul_lo_u32 v134, v133, s83
	v_sub_u32_e32 v132, v132, v134
	v_cmp_le_u32_e32 vcc, s83, v132
	v_add_u32_e32 v134, 1, v133
	v_ashrrev_i32_e32 v131, 31, v80
	v_cndmask_b32_e32 v133, v133, v134, vcc
	v_subrev_u32_e32 v134, s83, v132
	v_cndmask_b32_e32 v132, v132, v134, vcc
	v_cmp_le_u32_e32 vcc, s83, v132
	v_add_u32_e32 v132, 1, v133
	v_xor_b32_e32 v131, s87, v131
	v_cndmask_b32_e32 v132, v133, v132, vcc
	v_xor_b32_e32 v132, v132, v131
	v_sub_u32_e32 v132, v132, v131
	v_mul_lo_u32 v131, v132, s79
	v_sub_u32_e32 v138, v80, v131
	v_ashrrev_i32_e32 v131, 31, v130
	v_lshlrev_b64 v[130:131], s81, v[130:131]
	v_lshl_add_u64 v[130:131], v[130:131], 3, s[4:5]
	v_ashrrev_i32_e32 v133, 31, v132
	v_ashrrev_i32_e32 v139, 31, v138
	v_lshl_add_u64 v[140:141], v[132:133], 3, v[130:131]
	s_nop 1
	v_lshlrev_b64 v[202:203], s18, v[138:139]
	v_lshl_add_u64 v[204:205], v[202:203], 3, v[140:141]
	global_load_dwordx2 v[172:173], v[204:205], off
	v_add_u32_e32 v202, 1, v138
	v_ashrrev_i32_e32 v203, 31, v202
	v_lshlrev_b64 v[204:205], s18, v[202:203]
	v_lshl_add_u64 v[202:203], v[204:205], 3, v[140:141]
	global_load_dwordx2 v[174:175], v[202:203], off
	v_add_u32_e32 v202, 3, v138
	v_ashrrev_i32_e32 v203, 31, v202
	v_lshlrev_b64 v[204:205], s18, v[202:203]
	v_lshl_add_u64 v[202:203], v[204:205], 3, v[140:141]
	global_load_dwordx2 v[190:191], v[202:203], off
	v_add_u32_e32 v202, 5, v138
	v_ashrrev_i32_e32 v203, 31, v202
	v_lshlrev_b64 v[204:205], s18, v[202:203]
	v_lshl_add_u64 v[202:203], v[204:205], 3, v[140:141]
	global_load_dwordx2 v[192:193], v[202:203], off
	v_add_u32_e32 v202, 2, v138
	v_ashrrev_i32_e32 v203, 31, v202
	v_lshlrev_b64 v[204:205], s18, v[202:203]
	v_lshl_add_u64 v[202:203], v[204:205], 3, v[140:141]
	global_load_dwordx2 v[194:195], v[202:203], off
	v_add_u32_e32 v202, 4, v138
	v_ashrrev_i32_e32 v203, 31, v202
	v_lshlrev_b64 v[204:205], s18, v[202:203]
	v_lshl_add_u64 v[202:203], v[204:205], 3, v[140:141]
	global_load_dwordx2 v[196:197], v[202:203], off
	v_add_u32_e32 v202, 6, v138
	v_ashrrev_i32_e32 v203, 31, v202
	v_lshlrev_b64 v[204:205], s18, v[202:203]
	v_lshl_add_u64 v[202:203], v[204:205], 3, v[140:141]
	global_load_dwordx2 v[198:199], v[202:203], off
	v_add_u32_e32 v202, 7, v138
	v_ashrrev_i32_e32 v203, 31, v202
	v_lshlrev_b64 v[204:205], s18, v[202:203]
	v_lshl_add_u64 v[202:203], v[204:205], 3, v[140:141]
	global_load_dwordx2 v[200:201], v[202:203], off
	v_lshlrev_b64 v[130:131], s18, v[138:139]
	v_lshl_add_u64 v[130:131], v[130:131], 3, v[140:141]
	s_nop 0
	v_add_u32_e32 v132, 1, v138
	v_ashrrev_i32_e32 v133, 31, v132
	v_lshlrev_b64 v[132:133], s18, v[132:133]
	v_lshl_add_u64 v[132:133], v[132:133], 3, v[140:141]
	s_nop 0
	v_add_u32_e32 v134, 3, v138
	v_ashrrev_i32_e32 v135, 31, v134
	v_lshlrev_b64 v[134:135], s18, v[134:135]
	v_lshl_add_u64 v[134:135], v[134:135], 3, v[140:141]
	s_nop 0
	v_add_u32_e32 v142, 5, v138
	v_ashrrev_i32_e32 v143, 31, v142
	v_lshlrev_b64 v[142:143], s18, v[142:143]
	v_lshl_add_u64 v[142:143], v[142:143], 3, v[140:141]
	s_cmp_eq_u32 s96, s86
	s_mov_b64 s[38:39], s[36:37]
	s_nop 0
	s_waitcnt lgkmcnt(0)
; __device__ __forceinline__ float rinv_of(unsigned long long ss) { return rsqrtf((float)ss * (1.f / 16777216.f) * (1.f / DM) + 1e-6f); }
;   __device__ __forceinline__ void operator()(const f32x4 (&acc)[2][2][4][2], const Unit& u, const EpiCtx& x_, int wr, int wc, int fr, int fq) const {
;     ...
;         for (int i = 0; i < 8; ++i) cs[bj][i >> 2][i & 3] = rinv_of(sp[(size_t)(m0 + i) << lg]);
;     ...
;           const f32x4 v0 = acc[ai][bj][m][0] * cs[bj][0], v1 = acc[ai][bj][m][1] * cs[bj][1];
	s_nop 0
	s_waitcnt vmcnt(7)
	v_ffbh_u32_e32 v80, v173
	v_min_u32_e32 v80, 32, v80
	v_lshlrev_b64 v[130:131], v80, v[172:173]
	v_min_u32_e32 v130, 1, v130
	v_or_b32_e32 v130, v131, v130
	v_cvt_f32_u32_e32 v130, v130
	v_sub_u32_e32 v80, 32, v80
	v_ldexp_f32 v130, v130, v80
	s_nop 0
	s_waitcnt vmcnt(6)
	v_ffbh_u32_e32 v80, v175
	v_min_u32_e32 v80, 32, v80
	v_lshlrev_b64 v[132:133], v80, v[174:175]
	v_min_u32_e32 v131, 1, v132
	v_or_b32_e32 v131, v133, v131
	v_cvt_f32_u32_e32 v131, v131
	v_sub_u32_e32 v80, 32, v80
	v_ldexp_f32 v131, v131, v80
	v_pk_mul_f32 v[130:131], v[130:131], s[60:61] op_sel_hi:[1,0]
	s_nop 0
	v_pk_fma_f32 v[130:131], v[130:131], s[26:27], v[136:137] op_sel_hi:[1,0,0]
	s_nop 0
	v_mul_f32_e32 v80, 0x4b800000, v130
	v_cmp_gt_f32_e64 s[2:3], s50, v130
	v_cmp_gt_f32_e32 vcc, s50, v131
	s_nop 0
	v_cndmask_b32_e64 v80, v130, v80, s[2:3]
	v_rsq_f32_e32 v130, v80
	v_mul_f32_e32 v80, 0x4b800000, v131
	v_cndmask_b32_e32 v80, v131, v80, vcc
	v_rsq_f32_e32 v131, v80
	s_nop 0
	s_waitcnt vmcnt(5)
	v_ffbh_u32_e32 v80, v191
	v_min_u32_e32 v80, 32, v80
	v_lshlrev_b64 v[134:135], v80, v[190:191]
	v_pk_mul_f32 v[132:133], v[130:131], s[64:65] op_sel_hi:[1,0]
	v_min_u32_e32 v134, 1, v134
	v_cndmask_b32_e64 v130, v130, v132, s[2:3]
	v_add_u32_e32 v132, 2, v138
	v_cndmask_b32_e32 v131, v131, v133, vcc
	v_ashrrev_i32_e32 v133, 31, v132
	v_lshlrev_b64 v[132:133], s18, v[132:133]
	v_lshl_add_u64 v[132:133], v[132:133], 3, v[140:141]
	s_nop 0
	v_or_b32_e32 v134, v135, v134
	v_cvt_f32_u32_e32 v134, v134
	v_sub_u32_e32 v80, 32, v80
	v_pk_mul_f32 v[126:127], v[126:127], v[130:131]
	v_pk_mul_f32 v[110:111], v[110:111], v[130:131]
	v_ldexp_f32 v135, v134, v80
	v_cvt_pk_bf16_f32 v126, v126, v127
	v_pk_mul_f32 v[94:95], v[94:95], v[130:131]
	v_pk_mul_f32 v[76:77], v[76:77], v[130:131]
	v_pk_mul_f32 v[60:61], v[60:61], v[130:131]
	v_pk_mul_f32 v[44:45], v[44:45], v[130:131]
	v_pk_mul_f32 v[28:29], v[28:29], v[130:131]
	v_pk_mul_f32 v[12:13], v[12:13], v[130:131]
	s_waitcnt lgkmcnt(0)
	s_nop 0
	s_waitcnt vmcnt(3)
	v_ffbh_u32_e32 v80, v195
	v_min_u32_e32 v80, 32, v80
	v_lshlrev_b64 v[132:133], v80, v[194:195]
	v_min_u32_e32 v132, 1, v132
	v_or_b32_e32 v132, v133, v132
	v_cvt_f32_u32_e32 v132, v132
	v_sub_u32_e32 v80, 32, v80
	v_ldexp_f32 v134, v132, v80
	v_pk_mul_f32 v[132:133], v[134:135], s[60:61] op_sel_hi:[1,0]
	s_nop 0
	v_pk_fma_f32 v[132:133], v[132:133], s[26:27], v[136:137] op_sel_hi:[1,0,0]
	s_nop 0
	v_mul_f32_e32 v80, 0x4b800000, v132
	v_cmp_gt_f32_e64 s[2:3], s50, v132
	v_cmp_gt_f32_e32 vcc, s50, v133
	s_nop 0
	v_cndmask_b32_e64 v80, v132, v80, s[2:3]
	v_rsq_f32_e32 v132, v80
	v_mul_f32_e32 v80, 0x4b800000, v133
	v_cndmask_b32_e32 v80, v133, v80, vcc
	v_rsq_f32_e32 v133, v80
	v_ffbh_u32_e32 v80, v193
	v_min_u32_e32 v80, 32, v80
	v_lshlrev_b64 v[142:143], v80, v[192:193]
	v_pk_mul_f32 v[134:135], v[132:133], s[64:65] op_sel_hi:[1,0]
	v_min_u32_e32 v139, 1, v142
	v_cndmask_b32_e64 v132, v132, v134, s[2:3]
	v_add_u32_e32 v134, 4, v138
	v_cndmask_b32_e32 v133, v133, v135, vcc
	v_ashrrev_i32_e32 v135, 31, v134
	v_lshlrev_b64 v[134:135], s18, v[134:135]
	v_lshl_add_u64 v[134:135], v[134:135], 3, v[140:141]
	s_nop 0
	v_or_b32_e32 v139, v143, v139
	v_cvt_f32_u32_e32 v139, v139
	v_sub_u32_e32 v80, 32, v80
	v_pk_mul_f32 v[128:129], v[128:129], v[132:133]
	v_pk_mul_f32 v[112:113], v[112:113], v[132:133]
	v_ldexp_f32 v143, v139, v80
	v_cvt_pk_bf16_f32 v127, v128, v129
	v_pk_mul_f32 v[96:97], v[96:97], v[132:133]
	v_pk_mul_f32 v[78:79], v[78:79], v[132:133]
	v_pk_mul_f32 v[62:63], v[62:63], v[132:133]
	v_pk_mul_f32 v[46:47], v[46:47], v[132:133]
	v_pk_mul_f32 v[30:31], v[30:31], v[132:133]
	v_pk_mul_f32 v[14:15], v[14:15], v[132:133]
	s_waitcnt lgkmcnt(0)
	s_nop 0
	s_waitcnt vmcnt(2)
	v_ffbh_u32_e32 v80, v197
	v_min_u32_e32 v80, 32, v80
	v_lshlrev_b64 v[134:135], v80, v[196:197]
	v_min_u32_e32 v134, 1, v134
	v_or_b32_e32 v134, v135, v134
	v_cvt_f32_u32_e32 v134, v134
	v_sub_u32_e32 v80, 32, v80
	v_ldexp_f32 v142, v134, v80
	v_pk_mul_f32 v[134:135], v[142:143], s[60:61] op_sel_hi:[1,0]
	s_nop 0
	v_pk_fma_f32 v[134:135], v[134:135], s[26:27], v[136:137] op_sel_hi:[1,0,0]
	s_nop 0
	v_mul_f32_e32 v80, 0x4b800000, v134
	v_cmp_gt_f32_e64 s[2:3], s50, v134
	v_cmp_gt_f32_e32 vcc, s50, v135
	s_nop 0
	v_cndmask_b32_e64 v80, v134, v80, s[2:3]
	v_rsq_f32_e32 v134, v80
	v_mul_f32_e32 v80, 0x4b800000, v135
	v_cndmask_b32_e32 v80, v135, v80, vcc
	v_rsq_f32_e32 v135, v80
	s_nop 0
	v_pk_mul_f32 v[142:143], v[134:135], s[64:65] op_sel_hi:[1,0]
	s_nop 0
	v_cndmask_b32_e64 v134, v134, v142, s[2:3]
	v_add_u32_e32 v142, 6, v138
	v_add_u32_e32 v138, 7, v138
	v_cndmask_b32_e32 v135, v135, v143, vcc
	v_ashrrev_i32_e32 v143, 31, v142
	v_ashrrev_i32_e32 v139, 31, v138
	v_lshlrev_b64 v[142:143], s18, v[142:143]
	v_lshlrev_b64 v[138:139], s18, v[138:139]
	v_lshl_add_u64 v[142:143], v[142:143], 3, v[140:141]
	v_lshl_add_u64 v[138:139], v[138:139], 3, v[140:141]
	s_nop 0
	v_pk_mul_f32 v[122:123], v[122:123], v[134:135]
	s_nop 0
	v_cvt_pk_bf16_f32 v128, v122, v123
	v_ashrrev_i32_e32 v122, 5, v171
	v_ashrrev_i32_e32 v123, 31, v122
	v_lshlrev_b64 v[122:123], 13, v[122:123]
	v_lshl_add_u64 v[122:123], s[94:95], 0, v[122:123]
	s_waitcnt lgkmcnt(0)
	s_nop 0
	s_waitcnt vmcnt(0)
; __device__ __forceinline__ float rinv_of(unsigned long long ss) { return rsqrtf((float)ss * (1.f / 16777216.f) * (1.f / DM) + 1e-6f); }
;   __device__ __forceinline__ void operator()(const f32x4 (&acc)[2][2][4][2], const Unit& u, const EpiCtx& x_, int wr, int wc, int fr, int fq) const {
;     ...
;         const int col = u.c0 + wc * 64 + bj * 32 + 8 * fq, seq = col / S, rem = col % S, r = rem / L, m0 = rem % L;
;         const unsigned long long* sp = x_.ss + (size_t)seq * S + r;
; #pragma unroll
;         for (int i = 0; i < 8; ++i) cs[bj][i >> 2][i & 3] = rinv_of(sp[(size_t)(m0 + i) << lg]);
;       } }
	v_ffbh_u32_e32 v80, v201
	v_min_u32_e32 v80, 32, v80
	v_lshlrev_b64 v[138:139], v80, v[200:201]
	v_min_u32_e32 v138, 1, v138
	v_or_b32_e32 v138, v139, v138
	v_cvt_f32_u32_e32 v138, v138
	v_sub_u32_e32 v80, 32, v80
	v_ldexp_f32 v139, v138, v80
	v_ffbh_u32_e32 v80, v199
	v_min_u32_e32 v80, 32, v80
	v_lshlrev_b64 v[140:141], v80, v[198:199]
	v_min_u32_e32 v138, 1, v140
	v_or_b32_e32 v138, v141, v138
	v_cvt_f32_u32_e32 v138, v138
	v_sub_u32_e32 v80, 32, v80
	v_ldexp_f32 v138, v138, v80
	v_pk_mul_f32 v[138:139], v[138:139], s[60:61] op_sel_hi:[1,0]
	s_nop 0
	v_pk_fma_f32 v[138:139], v[138:139], s[26:27], v[136:137] op_sel_hi:[1,0,0]
	s_nop 0
	v_mul_f32_e32 v80, 0x4b800000, v138
	v_cmp_gt_f32_e64 s[2:3], s50, v138
	v_cmp_gt_f32_e32 vcc, s50, v139
	s_nop 0
	v_cndmask_b32_e64 v80, v138, v80, s[2:3]
	v_rsq_f32_e32 v138, v80
	v_mul_f32_e32 v80, 0x4b800000, v139
	v_cndmask_b32_e32 v80, v139, v80, vcc
	v_rsq_f32_e32 v139, v80
	v_add_u32_e32 v80, 32, v171
	v_pk_mul_f32 v[140:141], v[138:139], s[64:65] op_sel_hi:[1,0]
	s_nop 0
	v_cndmask_b32_e32 v139, v139, v141, vcc
	v_sub_u32_e32 v141, 0xffffffe0, v171
	v_max_i32_e32 v141, v80, v141
	v_mul_hi_u32 v142, v141, v152
	v_mul_lo_u32 v143, v142, s17
	v_sub_u32_e32 v141, v141, v143
	v_cmp_le_u32_e32 vcc, s17, v141
	v_add_u32_e32 v143, 1, v142
	v_cndmask_b32_e64 v138, v138, v140, s[2:3]
	v_cndmask_b32_e32 v142, v142, v143, vcc
	v_subrev_u32_e32 v143, s17, v141
	v_cndmask_b32_e32 v141, v141, v143, vcc
	v_cmp_le_u32_e32 vcc, s17, v141
	v_add_u32_e32 v141, 1, v142
	v_ashrrev_i32_e32 v140, 31, v80
	v_cndmask_b32_e32 v141, v142, v141, vcc
	v_xor_b32_e32 v141, v141, v140
	v_sub_u32_e32 v140, v141, v140
	v_mul_lo_u32 v141, v140, s17
	v_sub_u32_e32 v80, v80, v141
	v_sub_u32_e32 v142, 0, v80
	v_max_i32_e32 v142, v80, v142
	v_mul_hi_u32 v143, v142, v169
	v_mul_lo_u32 v144, v143, s83
	v_sub_u32_e32 v142, v142, v144
	v_cmp_le_u32_e32 vcc, s83, v142
	v_add_u32_e32 v144, 1, v143
	v_ashrrev_i32_e32 v141, 31, v80
	v_cndmask_b32_e32 v143, v143, v144, vcc
	v_subrev_u32_e32 v144, s83, v142
	v_cndmask_b32_e32 v142, v142, v144, vcc
	v_cmp_le_u32_e32 vcc, s83, v142
	v_add_u32_e32 v142, 1, v143
	v_xor_b32_e32 v141, s87, v141
	v_cndmask_b32_e32 v142, v143, v142, vcc
	v_xor_b32_e32 v142, v142, v141
	v_sub_u32_e32 v142, v142, v141
	v_mul_lo_u32 v141, v142, s79
	v_sub_u32_e32 v146, v80, v141
	v_ashrrev_i32_e32 v141, 31, v140
	v_lshlrev_b64 v[140:141], s81, v[140:141]
	v_lshl_add_u64 v[140:141], v[140:141], 3, s[4:5]
	v_ashrrev_i32_e32 v143, 31, v142
	v_ashrrev_i32_e32 v147, 31, v146
	v_lshl_add_u64 v[148:149], v[142:143], 3, v[140:141]
	v_lshlrev_b64 v[140:141], s18, v[146:147]
	v_lshl_add_u64 v[140:141], v[140:141], 3, v[148:149]
	s_nop 1
	global_load_dwordx2 v[172:173], v[140:141], off
	v_add_u32_e32 v202, 1, v146
	v_ashrrev_i32_e32 v203, 31, v202
	v_lshlrev_b64 v[204:205], s18, v[202:203]
	v_lshl_add_u64 v[202:203], v[204:205], 3, v[148:149]
	global_load_dwordx2 v[174:175], v[202:203], off
	v_add_u32_e32 v202, 3, v146
	v_ashrrev_i32_e32 v203, 31, v202
	v_lshlrev_b64 v[204:205], s18, v[202:203]
	v_lshl_add_u64 v[202:203], v[204:205], 3, v[148:149]
	global_load_dwordx2 v[190:191], v[202:203], off
	v_add_u32_e32 v202, 5, v146
	v_ashrrev_i32_e32 v203, 31, v202
	v_lshlrev_b64 v[204:205], s18, v[202:203]
	v_lshl_add_u64 v[202:203], v[204:205], 3, v[148:149]
	global_load_dwordx2 v[192:193], v[202:203], off
	v_add_u32_e32 v202, 2, v146
	v_ashrrev_i32_e32 v203, 31, v202
	v_lshlrev_b64 v[204:205], s18, v[202:203]
	v_lshl_add_u64 v[202:203], v[204:205], 3, v[148:149]
	global_load_dwordx2 v[194:195], v[202:203], off
	v_add_u32_e32 v202, 4, v146
	v_ashrrev_i32_e32 v203, 31, v202
	v_lshlrev_b64 v[204:205], s18, v[202:203]
	v_lshl_add_u64 v[202:203], v[204:205], 3, v[148:149]
	global_load_dwordx2 v[196:197], v[202:203], off
	v_add_u32_e32 v202, 6, v146
	v_ashrrev_i32_e32 v203, 31, v202
	v_lshlrev_b64 v[204:205], s18, v[202:203]
	v_lshl_add_u64 v[202:203], v[204:205], 3, v[148:149]
	global_load_dwordx2 v[198:199], v[202:203], off
	v_add_u32_e32 v202, 7, v146
	v_ashrrev_i32_e32 v203, 31, v202
	v_lshlrev_b64 v[204:205], s18, v[202:203]
	v_lshl_add_u64 v[202:203], v[204:205], 3, v[148:149]
	global_load_dwordx2 v[200:201], v[202:203], off
	s_nop 0
	v_add_u32_e32 v142, 1, v146
	v_ashrrev_i32_e32 v143, 31, v142
	v_lshlrev_b64 v[142:143], s18, v[142:143]
	v_lshl_add_u64 v[142:143], v[142:143], 3, v[148:149]
	s_nop 0
	v_add_u32_e32 v144, 3, v146
	v_ashrrev_i32_e32 v145, 31, v144
	v_lshlrev_b64 v[144:145], s18, v[144:145]
	v_lshl_add_u64 v[144:145], v[144:145], 3, v[148:149]
	s_nop 0
	v_add_u32_e32 v150, 5, v146
	v_ashrrev_i32_e32 v151, 31, v150
	v_lshlrev_b64 v[150:151], s18, v[150:151]
	v_lshl_add_u64 v[150:151], v[150:151], 3, v[148:149]
	v_pk_mul_f32 v[124:125], v[124:125], v[138:139]
	s_nop 0
	v_cvt_pk_bf16_f32 v129, v124, v125
	s_waitcnt lgkmcnt(0)
	s_nop 0
	s_waitcnt vmcnt(7)
	v_ffbh_u32_e32 v80, v173
	v_min_u32_e32 v80, 32, v80
	v_lshlrev_b64 v[140:141], v80, v[172:173]
	v_min_u32_e32 v140, 1, v140
	v_or_b32_e32 v140, v141, v140
	v_cvt_f32_u32_e32 v140, v140
	v_sub_u32_e32 v80, 32, v80
	v_ldexp_f32 v140, v140, v80
	s_nop 0
	s_waitcnt vmcnt(6)
	v_ffbh_u32_e32 v80, v175
	v_min_u32_e32 v80, 32, v80
	v_lshlrev_b64 v[142:143], v80, v[174:175]
	v_min_u32_e32 v141, 1, v142
	v_or_b32_e32 v141, v143, v141
	v_cvt_f32_u32_e32 v141, v141
	v_sub_u32_e32 v80, 32, v80
	v_ldexp_f32 v141, v141, v80
	v_pk_mul_f32 v[140:141], v[140:141], s[60:61] op_sel_hi:[1,0]
	s_nop 0
	v_pk_fma_f32 v[140:141], v[140:141], s[26:27], v[136:137] op_sel_hi:[1,0,0]
	s_nop 0
	v_mul_f32_e32 v80, 0x4b800000, v140
	v_cmp_gt_f32_e64 s[2:3], s50, v140
	v_cmp_gt_f32_e32 vcc, s50, v141
	s_nop 0
	v_cndmask_b32_e64 v80, v140, v80, s[2:3]
	v_rsq_f32_e32 v140, v80
	v_mul_f32_e32 v80, 0x4b800000, v141
	v_cndmask_b32_e32 v80, v141, v80, vcc
	v_rsq_f32_e32 v141, v80
	s_nop 0
	s_waitcnt vmcnt(5)
; __device__ __forceinline__ unsigned cvt_pk_bf16(float lo, float hi) { unsigned r; asm("v_cvt_pk_bf16_f32 %0, %1, %2" : "=v"(r) : "v"(lo), "v"(hi)); return r; }
; __device__ __forceinline__ float rinv_of(unsigned long long ss) { return rsqrtf((float)ss * (1.f / 16777216.f) * (1.f / DM) + 1e-6f); }
;   __device__ __forceinline__ void operator()(const f32x4 (&acc)[2][2][4][2], const Unit& u, const EpiCtx& x_, int wr, int wc, int fr, int fq) const {
;     ...
;         for (int i = 0; i < 8; ++i) cs[bj][i >> 2][i & 3] = rinv_of(sp[(size_t)(m0 + i) << lg]);
;       } }
; #pragma unroll
;     for (int ai = 0; ai < 2; ++ai)
; #pragma unroll
;       for (int m = 0; m < 4; ++m) {
;         const int row = u.r0 + ai * 128 + wr * 64 + m * 16 + fr, hh = (x_.p0 >> 1) * 16 + (row >> 7), d = row & 127;
; #pragma unroll
;         for (int bj = 0; bj < 2; ++bj) {
;           const int col = u.c0 + wc * 64 + bj * 32 + 8 * fq;
;           const f32x4 v0 = acc[ai][bj][m][0] * cs[bj][0], v1 = acc[ai][bj][m][1] * cs[bj][1];
;           uint4 o; o.x = cvt_pk_bf16(v0[0], v0[1]); o.y = cvt_pk_bf16(v0[2], v0[3]); o.z = cvt_pk_bf16(v1[0], v1[1]); o.w = cvt_pk_bf16(v1[2], v1[3]);
;           *(uint4*)((bf16_t*)u.C + (((size_t)hh * (TS / 32) + (col >> 5)) * 128 + d) * 32 + (col & 31)) = o;
	v_ffbh_u32_e32 v80, v191
	v_min_u32_e32 v80, 32, v80
	v_lshlrev_b64 v[144:145], v80, v[190:191]
	v_pk_mul_f32 v[142:143], v[140:141], s[64:65] op_sel_hi:[1,0]
	v_min_u32_e32 v144, 1, v144
	v_cndmask_b32_e64 v140, v140, v142, s[2:3]
	v_add_u32_e32 v142, 2, v146
	v_cndmask_b32_e32 v141, v141, v143, vcc
	v_ashrrev_i32_e32 v143, 31, v142
	v_lshlrev_b64 v[142:143], s18, v[142:143]
	v_lshl_add_u64 v[142:143], v[142:143], 3, v[148:149]
	s_nop 0
	v_or_b32_e32 v144, v145, v144
	v_cvt_f32_u32_e32 v144, v144
	v_sub_u32_e32 v80, 32, v80
	v_pk_mul_f32 v[118:119], v[118:119], v[140:141]
	v_pk_mul_f32 v[102:103], v[102:103], v[140:141]
	v_ldexp_f32 v145, v144, v80
	v_pk_mul_f32 v[86:87], v[86:87], v[140:141]
	v_pk_mul_f32 v[68:69], v[68:69], v[140:141]
	v_pk_mul_f32 v[52:53], v[52:53], v[140:141]
	v_pk_mul_f32 v[36:37], v[36:37], v[140:141]
	v_pk_mul_f32 v[20:21], v[20:21], v[140:141]
	v_pk_mul_f32 v[4:5], v[4:5], v[140:141]
	s_waitcnt lgkmcnt(0)
	s_nop 0
	s_waitcnt vmcnt(3)
	v_ffbh_u32_e32 v80, v195
	v_min_u32_e32 v80, 32, v80
	v_lshlrev_b64 v[142:143], v80, v[194:195]
	v_min_u32_e32 v142, 1, v142
	v_or_b32_e32 v142, v143, v142
	v_cvt_f32_u32_e32 v142, v142
	v_sub_u32_e32 v80, 32, v80
	v_ldexp_f32 v144, v142, v80
	v_pk_mul_f32 v[142:143], v[144:145], s[60:61] op_sel_hi:[1,0]
	s_nop 0
	v_pk_fma_f32 v[142:143], v[142:143], s[26:27], v[136:137] op_sel_hi:[1,0,0]
	s_nop 0
	v_mul_f32_e32 v80, 0x4b800000, v142
	v_cmp_gt_f32_e64 s[2:3], s50, v142
	v_cmp_gt_f32_e32 vcc, s50, v143
	s_nop 0
	v_cndmask_b32_e64 v80, v142, v80, s[2:3]
	v_rsq_f32_e32 v142, v80
	v_mul_f32_e32 v80, 0x4b800000, v143
	v_cndmask_b32_e32 v80, v143, v80, vcc
	v_rsq_f32_e32 v143, v80
	v_ffbh_u32_e32 v80, v193
	v_min_u32_e32 v80, 32, v80
	v_lshlrev_b64 v[150:151], v80, v[192:193]
	v_pk_mul_f32 v[144:145], v[142:143], s[64:65] op_sel_hi:[1,0]
	v_min_u32_e32 v147, 1, v150
	v_cndmask_b32_e64 v142, v142, v144, s[2:3]
	v_add_u32_e32 v144, 4, v146
	v_cndmask_b32_e32 v143, v143, v145, vcc
	v_ashrrev_i32_e32 v145, 31, v144
	v_lshlrev_b64 v[144:145], s18, v[144:145]
	v_lshl_add_u64 v[144:145], v[144:145], 3, v[148:149]
	s_nop 0
	v_or_b32_e32 v147, v151, v147
	v_cvt_f32_u32_e32 v147, v147
	v_sub_u32_e32 v80, 32, v80
	v_pk_mul_f32 v[120:121], v[120:121], v[142:143]
	v_pk_mul_f32 v[104:105], v[104:105], v[142:143]
	v_ldexp_f32 v151, v147, v80
	v_pk_mul_f32 v[88:89], v[88:89], v[142:143]
	v_pk_mul_f32 v[70:71], v[70:71], v[142:143]
	v_pk_mul_f32 v[54:55], v[54:55], v[142:143]
	v_pk_mul_f32 v[38:39], v[38:39], v[142:143]
	v_pk_mul_f32 v[22:23], v[22:23], v[142:143]
	v_pk_mul_f32 v[6:7], v[6:7], v[142:143]
	s_waitcnt lgkmcnt(0)
	s_nop 0
	s_waitcnt vmcnt(2)
	v_ffbh_u32_e32 v80, v197
	v_min_u32_e32 v80, 32, v80
	v_lshlrev_b64 v[144:145], v80, v[196:197]
	v_min_u32_e32 v144, 1, v144
	v_or_b32_e32 v144, v145, v144
	v_cvt_f32_u32_e32 v144, v144
	v_sub_u32_e32 v80, 32, v80
	v_ldexp_f32 v150, v144, v80
	v_pk_mul_f32 v[144:145], v[150:151], s[60:61] op_sel_hi:[1,0]
	s_nop 0
	v_pk_fma_f32 v[144:145], v[144:145], s[26:27], v[136:137] op_sel_hi:[1,0,0]
	s_nop 0
	v_mul_f32_e32 v80, 0x4b800000, v144
	v_cmp_gt_f32_e64 s[2:3], s50, v144
	v_cmp_gt_f32_e32 vcc, s50, v145
	s_nop 0
	v_cndmask_b32_e64 v80, v144, v80, s[2:3]
	v_rsq_f32_e32 v144, v80
	v_mul_f32_e32 v80, 0x4b800000, v145
	v_cndmask_b32_e32 v80, v145, v80, vcc
	v_rsq_f32_e32 v145, v80
	s_nop 0
	v_pk_mul_f32 v[150:151], v[144:145], s[64:65] op_sel_hi:[1,0]
	s_nop 0
	v_cndmask_b32_e64 v144, v144, v150, s[2:3]
	v_add_u32_e32 v150, 6, v146
	v_add_u32_e32 v146, 7, v146
	v_cndmask_b32_e32 v145, v145, v151, vcc
	v_ashrrev_i32_e32 v151, 31, v150
	v_ashrrev_i32_e32 v147, 31, v146
	v_lshlrev_b64 v[150:151], s18, v[150:151]
	v_lshlrev_b64 v[146:147], s18, v[146:147]
	v_lshl_add_u64 v[150:151], v[150:151], 3, v[148:149]
	v_lshl_add_u64 v[146:147], v[146:147], 3, v[148:149]
	s_nop 0
	v_pk_mul_f32 v[114:115], v[114:115], v[144:145]
	s_nop 0
	s_waitcnt lgkmcnt(0)
	s_nop 0
	s_waitcnt vmcnt(0)
	v_ffbh_u32_e32 v80, v201
	v_min_u32_e32 v80, 32, v80
	v_lshlrev_b64 v[146:147], v80, v[200:201]
	v_min_u32_e32 v146, 1, v146
	v_or_b32_e32 v146, v147, v146
	v_cvt_f32_u32_e32 v146, v146
	v_sub_u32_e32 v80, 32, v80
	v_ldexp_f32 v147, v146, v80
	v_ffbh_u32_e32 v80, v199
	v_min_u32_e32 v80, 32, v80
	v_lshlrev_b64 v[148:149], v80, v[198:199]
	v_min_u32_e32 v146, 1, v148
	v_or_b32_e32 v146, v149, v146
	v_cvt_f32_u32_e32 v146, v146
	v_sub_u32_e32 v80, 32, v80
	v_ldexp_f32 v146, v146, v80
	v_pk_mul_f32 v[146:147], v[146:147], s[60:61] op_sel_hi:[1,0]
	s_nop 0
	v_pk_fma_f32 v[136:137], v[146:147], s[26:27], v[136:137] op_sel_hi:[1,0,0]
	s_nop 0
	v_mul_f32_e32 v80, 0x4b800000, v136
	v_cmp_gt_f32_e64 s[2:3], s50, v136
	v_cmp_gt_f32_e32 vcc, s50, v137
	s_nop 0
	v_cndmask_b32_e64 v80, v136, v80, s[2:3]
	v_rsq_f32_e32 v136, v80
	v_mul_f32_e32 v80, 0x4b800000, v137
	v_cndmask_b32_e32 v80, v137, v80, vcc
	v_rsq_f32_e32 v137, v80
	v_add_u32_e32 v80, s75, v157
	v_pk_mul_f32 v[146:147], v[136:137], s[64:65] op_sel_hi:[1,0]
	s_nop 0
	v_cndmask_b32_e64 v136, v136, v146, s[2:3]
	v_ashrrev_i32_e32 v146, 7, v80
	v_add_u32_e32 v146, s82, v146
	v_cndmask_b32_e32 v137, v137, v147, vcc
	v_ashrrev_i32_e32 v147, 31, v146
	v_lshlrev_b64 v[146:147], 22, v[146:147]
	v_lshlrev_b32_e32 v80, 6, v80
	v_and_b32_e32 v80, 0x1fc0, v80
	v_lshl_add_u64 v[124:125], v[122:123], 0, v[146:147]
	v_lshl_add_u64 v[148:149], v[124:125], 0, v[80:81]
	v_and_b32_e32 v124, 31, v171
	v_lshlrev_b32_e32 v124, 1, v124
	v_mov_b32_e32 v125, v81
	v_lshl_add_u64 v[148:149], v[148:149], 0, v[124:125]
	global_store_dwordx4 v[148:149], v[126:129], off
	s_mov_b64 s[2:3], s[8:9]
	s_nop 0
	v_add_u32_e32 v128, s97, v160
	v_pk_mul_f32 v[126:127], v[116:117], v[136:137]
; __device__ __forceinline__ unsigned cvt_pk_bf16(float lo, float hi) { unsigned r; asm("v_cvt_pk_bf16_f32 %0, %1, %2" : "=v"(r) : "v"(lo), "v"(hi)); return r; }
;   __device__ __forceinline__ void operator()(const f32x4 (&acc)[2][2][4][2], const Unit& u, const EpiCtx& x_, int wr, int wc, int fr, int fq) const {
;     ...
;     for (int ai = 0; ai < 2; ++ai)
; #pragma unroll
;       for (int m = 0; m < 4; ++m) {
;         const int row = u.r0 + ai * 128 + wr * 64 + m * 16 + fr, hh = (x_.p0 >> 1) * 16 + (row >> 7), d = row & 127;
; #pragma unroll
;         for (int bj = 0; bj < 2; ++bj) {
;           const int col = u.c0 + wc * 64 + bj * 32 + 8 * fq;
;           const f32x4 v0 = acc[ai][bj][m][0] * cs[bj][0], v1 = acc[ai][bj][m][1] * cs[bj][1];
;           uint4 o; o.x = cvt_pk_bf16(v0[0], v0[1]); o.y = cvt_pk_bf16(v0[2], v0[3]); o.z = cvt_pk_bf16(v1[0], v1[1]); o.w = cvt_pk_bf16(v1[2], v1[3]);
;           *(uint4*)((bf16_t*)u.C + (((size_t)hh * (TS / 32) + (col >> 5)) * 128 + d) * 32 + (col & 31)) = o;
;         }
	v_cvt_pk_bf16_f32 v116, v118, v119
	v_cvt_pk_bf16_f32 v118, v114, v115
	v_ashrrev_i32_e32 v114, 5, v128
	v_ashrrev_i32_e32 v115, 31, v114
	v_lshlrev_b64 v[114:115], 13, v[114:115]
	v_lshl_add_u64 v[114:115], s[94:95], 0, v[114:115]
	v_cvt_pk_bf16_f32 v117, v120, v121
	v_lshl_add_u64 v[120:121], v[114:115], 0, v[146:147]
	v_lshl_add_u64 v[120:121], v[120:121], 0, v[80:81]
	v_and_b32_e32 v80, 31, v128
	v_lshlrev_b32_e32 v80, 1, v80
	v_lshl_add_u64 v[120:121], v[120:121], 0, v[80:81]
	v_cvt_pk_bf16_f32 v119, v126, v127
	global_store_dwordx4 v[120:121], v[116:119], off
	v_add_u32_e32 v120, s75, v161
	s_mov_b64 s[94:95], s[40:41]
	v_ashrrev_i32_e32 v116, 7, v120
	v_add_u32_e32 v116, s82, v116
	v_ashrrev_i32_e32 v117, 31, v116
	v_pk_mul_f32 v[118:119], v[108:109], v[138:139]
	v_pk_mul_f32 v[108:109], v[106:107], v[134:135]
	v_cvt_pk_bf16_f32 v106, v110, v111
	v_cvt_pk_bf16_f32 v107, v112, v113
	v_lshlrev_b64 v[110:111], 22, v[116:117]
	v_lshlrev_b32_e32 v112, 6, v120
	v_and_b32_e32 v112, 0x1fc0, v112
	v_mov_b32_e32 v113, v81
	v_lshl_add_u64 v[116:117], v[122:123], 0, v[110:111]
	v_lshl_add_u64 v[116:117], v[116:117], 0, v[112:113]
	v_lshl_add_u64 v[116:117], v[116:117], 0, v[124:125]
	v_cvt_pk_bf16_f32 v108, v108, v109
	v_cvt_pk_bf16_f32 v109, v118, v119
	global_store_dwordx4 v[116:117], v[106:109], off
	s_mov_b32 s97, s42
	s_nop 0
	v_pk_mul_f32 v[106:107], v[100:101], v[136:137]
	v_pk_mul_f32 v[100:101], v[98:99], v[144:145]
	v_cvt_pk_bf16_f32 v98, v102, v103
	v_lshl_add_u64 v[102:103], v[114:115], 0, v[110:111]
	v_lshl_add_u64 v[102:103], v[102:103], 0, v[112:113]
	v_lshl_add_u64 v[102:103], v[102:103], 0, v[80:81]
	v_cvt_pk_bf16_f32 v99, v104, v105
	v_cvt_pk_bf16_f32 v100, v100, v101
	v_cvt_pk_bf16_f32 v101, v106, v107
	global_store_dwordx4 v[102:103], v[98:101], off
	v_add_u32_e32 v102, s75, v163
	s_nop 0
	v_ashrrev_i32_e32 v98, 7, v102
	v_add_u32_e32 v98, s82, v98
	v_ashrrev_i32_e32 v99, 31, v98
	v_pk_mul_f32 v[100:101], v[92:93], v[138:139]
	v_pk_mul_f32 v[92:93], v[90:91], v[134:135]
	v_cvt_pk_bf16_f32 v90, v94, v95
	v_cvt_pk_bf16_f32 v91, v96, v97
	v_lshlrev_b64 v[94:95], 22, v[98:99]
	v_lshlrev_b32_e32 v96, 6, v102
	v_and_b32_e32 v96, 0x1fc0, v96
	v_mov_b32_e32 v97, v81
	v_lshl_add_u64 v[98:99], v[122:123], 0, v[94:95]
	v_lshl_add_u64 v[98:99], v[98:99], 0, v[96:97]
	v_lshl_add_u64 v[98:99], v[98:99], 0, v[124:125]
	v_cvt_pk_bf16_f32 v92, v92, v93
	v_cvt_pk_bf16_f32 v93, v100, v101
	global_store_dwordx4 v[98:99], v[90:93], off
	s_nop 1
	v_pk_mul_f32 v[90:91], v[84:85], v[136:137]
	v_pk_mul_f32 v[84:85], v[82:83], v[144:145]
	v_cvt_pk_bf16_f32 v82, v86, v87
	v_lshl_add_u64 v[86:87], v[114:115], 0, v[94:95]
	v_lshl_add_u64 v[86:87], v[86:87], 0, v[96:97]
	v_lshl_add_u64 v[86:87], v[86:87], 0, v[80:81]
	v_cvt_pk_bf16_f32 v83, v88, v89
	v_cvt_pk_bf16_f32 v84, v84, v85
	v_cvt_pk_bf16_f32 v85, v90, v91
	global_store_dwordx4 v[86:87], v[82:85], off
	v_add_u32_e32 v86, s75, v164
	s_nop 0
	v_ashrrev_i32_e32 v82, 7, v86
	v_add_u32_e32 v82, s82, v82
	v_ashrrev_i32_e32 v83, 31, v82
	v_pk_mul_f32 v[84:85], v[74:75], v[138:139]
	v_pk_mul_f32 v[74:75], v[72:73], v[134:135]
	v_cvt_pk_bf16_f32 v72, v76, v77
	v_cvt_pk_bf16_f32 v73, v78, v79
	v_lshlrev_b64 v[76:77], 22, v[82:83]
	v_lshlrev_b32_e32 v78, 6, v86
	v_and_b32_e32 v78, 0x1fc0, v78
	v_mov_b32_e32 v79, v81
	v_lshl_add_u64 v[82:83], v[122:123], 0, v[76:77]
	v_lshl_add_u64 v[82:83], v[82:83], 0, v[78:79]
	v_lshl_add_u64 v[82:83], v[82:83], 0, v[124:125]
	v_cvt_pk_bf16_f32 v74, v74, v75
	v_cvt_pk_bf16_f32 v75, v84, v85
	global_store_dwordx4 v[82:83], v[72:75], off
	s_nop 1
	v_pk_mul_f32 v[72:73], v[66:67], v[136:137]
	v_pk_mul_f32 v[66:67], v[64:65], v[144:145]
	v_cvt_pk_bf16_f32 v64, v68, v69
	v_lshl_add_u64 v[68:69], v[114:115], 0, v[76:77]
	v_lshl_add_u64 v[68:69], v[68:69], 0, v[78:79]
	v_lshl_add_u64 v[68:69], v[68:69], 0, v[80:81]
	v_cvt_pk_bf16_f32 v65, v70, v71
	v_cvt_pk_bf16_f32 v66, v66, v67
	v_cvt_pk_bf16_f32 v67, v72, v73
	global_store_dwordx4 v[68:69], v[64:67], off
	v_add_u32_e32 v68, s75, v165
	s_nop 0
	v_ashrrev_i32_e32 v64, 7, v68
	v_add_u32_e32 v64, s82, v64
	v_ashrrev_i32_e32 v65, 31, v64
	v_pk_mul_f32 v[66:67], v[58:59], v[138:139]
	v_pk_mul_f32 v[58:59], v[56:57], v[134:135]
	v_cvt_pk_bf16_f32 v56, v60, v61
; __device__ __forceinline__ unsigned cvt_pk_bf16(float lo, float hi) { unsigned r; asm("v_cvt_pk_bf16_f32 %0, %1, %2" : "=v"(r) : "v"(lo), "v"(hi)); return r; }
; #define G_WAIT_V(n) asm volatile("s_waitcnt vmcnt(" #n ")" ::: "memory")
; #define G_BAR __builtin_amdgcn_s_barrier()
;   __device__ __forceinline__ void operator()(const f32x4 (&acc)[2][2][4][2], const Unit& u, const EpiCtx& x_, int wr, int wc, int fr, int fq) const {
;     ...
; #pragma unroll
;     for (int ai = 0; ai < 2; ++ai)
; #pragma unroll
;       for (int m = 0; m < 4; ++m) {
;         const int row = u.r0 + ai * 128 + wr * 64 + m * 16 + fr, hh = (x_.p0 >> 1) * 16 + (row >> 7), d = row & 127;
; #pragma unroll
;         for (int bj = 0; bj < 2; ++bj) {
;           const int col = u.c0 + wc * 64 + bj * 32 + 8 * fq;
;           const f32x4 v0 = acc[ai][bj][m][0] * cs[bj][0], v1 = acc[ai][bj][m][1] * cs[bj][1];
;           uint4 o; o.x = cvt_pk_bf16(v0[0], v0[1]); o.y = cvt_pk_bf16(v0[2], v0[3]); o.z = cvt_pk_bf16(v1[0], v1[1]); o.w = cvt_pk_bf16(v1[2], v1[3]);
;           *(uint4*)((bf16_t*)u.C + (((size_t)hh * (TS / 32) + (col >> 5)) * 128 + d) * 32 + (col & 31)) = o;
;         }
;       }
; template <class Epi>
; __device__ __forceinline__ void gemm_phase(LAS unsigned char* lds, const int K, const unsigned lda_b, const unsigned ldb_b, const Map& M, const Epi& E) {
;     ...
;     E(acc, cur, X, wr, wc, fr, fq);
;     if (!has_next) break;
; #pragma unroll
;     for (int a = 0; a < 2; ++a)
; #pragma unroll
;       for (int b = 0; b < 2; ++b)
; #pragma unroll
;         for (int m = 0; m < 4; ++m)
; #pragma unroll
;           for (int n = 0; n < 2; ++n) acc[a][b][m][n] = (f32x4){0.f, 0.f, 0.f, 0.f};
;     cur = nxt; ++ui;
;   }
;   G_WAIT_V(0);
;   if (wr == 0) G_BAR;
;   G_BAR;
	v_cvt_pk_bf16_f32 v57, v62, v63
	v_lshlrev_b64 v[60:61], 22, v[64:65]
	v_lshlrev_b32_e32 v62, 6, v68
	v_and_b32_e32 v62, 0x1fc0, v62
	v_mov_b32_e32 v63, v81
	v_lshl_add_u64 v[64:65], v[122:123], 0, v[60:61]
	v_lshl_add_u64 v[64:65], v[64:65], 0, v[62:63]
	v_lshl_add_u64 v[64:65], v[64:65], 0, v[124:125]
	v_cvt_pk_bf16_f32 v58, v58, v59
	v_cvt_pk_bf16_f32 v59, v66, v67
	global_store_dwordx4 v[64:65], v[56:59], off
	s_nop 1
	v_pk_mul_f32 v[56:57], v[50:51], v[136:137]
	v_pk_mul_f32 v[50:51], v[48:49], v[144:145]
	v_cvt_pk_bf16_f32 v48, v52, v53
	v_lshl_add_u64 v[52:53], v[114:115], 0, v[60:61]
	v_lshl_add_u64 v[52:53], v[52:53], 0, v[62:63]
	v_lshl_add_u64 v[52:53], v[52:53], 0, v[80:81]
	v_cvt_pk_bf16_f32 v49, v54, v55
	v_cvt_pk_bf16_f32 v50, v50, v51
	v_cvt_pk_bf16_f32 v51, v56, v57
	global_store_dwordx4 v[52:53], v[48:51], off
	v_add_u32_e32 v52, s75, v166
	s_nop 0
	v_ashrrev_i32_e32 v48, 7, v52
	v_add_u32_e32 v48, s82, v48
	v_ashrrev_i32_e32 v49, 31, v48
	v_pk_mul_f32 v[50:51], v[42:43], v[138:139]
	v_pk_mul_f32 v[42:43], v[40:41], v[134:135]
	v_cvt_pk_bf16_f32 v40, v44, v45
	v_cvt_pk_bf16_f32 v41, v46, v47
	v_lshlrev_b64 v[44:45], 22, v[48:49]
	v_lshlrev_b32_e32 v46, 6, v52
	v_and_b32_e32 v46, 0x1fc0, v46
	v_mov_b32_e32 v47, v81
	v_lshl_add_u64 v[48:49], v[122:123], 0, v[44:45]
	v_lshl_add_u64 v[48:49], v[48:49], 0, v[46:47]
	v_lshl_add_u64 v[48:49], v[48:49], 0, v[124:125]
	v_cvt_pk_bf16_f32 v42, v42, v43
	v_cvt_pk_bf16_f32 v43, v50, v51
	global_store_dwordx4 v[48:49], v[40:43], off
	s_nop 1
	v_pk_mul_f32 v[40:41], v[34:35], v[136:137]
	v_pk_mul_f32 v[34:35], v[32:33], v[144:145]
	v_cvt_pk_bf16_f32 v32, v36, v37
	v_lshl_add_u64 v[36:37], v[114:115], 0, v[44:45]
	v_lshl_add_u64 v[36:37], v[36:37], 0, v[46:47]
	v_lshl_add_u64 v[36:37], v[36:37], 0, v[80:81]
	v_cvt_pk_bf16_f32 v33, v38, v39
	v_cvt_pk_bf16_f32 v34, v34, v35
	v_cvt_pk_bf16_f32 v35, v40, v41
	global_store_dwordx4 v[36:37], v[32:35], off
	v_add_u32_e32 v36, s75, v167
	s_nop 0
	v_ashrrev_i32_e32 v32, 7, v36
	v_add_u32_e32 v32, s82, v32
	v_ashrrev_i32_e32 v33, 31, v32
	v_pk_mul_f32 v[34:35], v[26:27], v[138:139]
	v_pk_mul_f32 v[26:27], v[24:25], v[134:135]
	v_cvt_pk_bf16_f32 v24, v28, v29
	v_cvt_pk_bf16_f32 v25, v30, v31
	v_lshlrev_b64 v[28:29], 22, v[32:33]
	v_lshlrev_b32_e32 v30, 6, v36
	v_and_b32_e32 v30, 0x1fc0, v30
	v_mov_b32_e32 v31, v81
	v_lshl_add_u64 v[32:33], v[122:123], 0, v[28:29]
	v_lshl_add_u64 v[32:33], v[32:33], 0, v[30:31]
	v_lshl_add_u64 v[32:33], v[32:33], 0, v[124:125]
	v_cvt_pk_bf16_f32 v26, v26, v27
	v_cvt_pk_bf16_f32 v27, v34, v35
	global_store_dwordx4 v[32:33], v[24:27], off
	s_nop 1
	v_pk_mul_f32 v[24:25], v[18:19], v[136:137]
	v_pk_mul_f32 v[18:19], v[16:17], v[144:145]
	v_cvt_pk_bf16_f32 v16, v20, v21
	v_lshl_add_u64 v[20:21], v[114:115], 0, v[28:29]
	v_lshl_add_u64 v[20:21], v[20:21], 0, v[30:31]
	v_lshl_add_u64 v[20:21], v[20:21], 0, v[80:81]
	v_cvt_pk_bf16_f32 v17, v22, v23
	v_cvt_pk_bf16_f32 v18, v18, v19
	v_cvt_pk_bf16_f32 v19, v24, v25
	global_store_dwordx4 v[20:21], v[16:19], off
	v_add_u32_e32 v20, s75, v168
	s_mov_b32 s75, s0
	v_ashrrev_i32_e32 v16, 7, v20
	v_add_u32_e32 v16, s82, v16
	v_ashrrev_i32_e32 v17, 31, v16
	v_pk_mul_f32 v[18:19], v[10:11], v[138:139]
	v_pk_mul_f32 v[10:11], v[8:9], v[134:135]
	v_cvt_pk_bf16_f32 v8, v12, v13
	v_cvt_pk_bf16_f32 v9, v14, v15
	v_lshlrev_b64 v[12:13], 22, v[16:17]
	v_lshlrev_b32_e32 v14, 6, v20
	v_and_b32_e32 v14, 0x1fc0, v14
	v_mov_b32_e32 v15, v81
	v_lshl_add_u64 v[16:17], v[122:123], 0, v[12:13]
	v_lshl_add_u64 v[16:17], v[16:17], 0, v[14:15]
	v_lshl_add_u64 v[16:17], v[16:17], 0, v[124:125]
	v_cvt_pk_bf16_f32 v10, v10, v11
	v_cvt_pk_bf16_f32 v11, v18, v19
	global_store_dwordx4 v[16:17], v[8:11], off
	s_nop 1
	v_pk_mul_f32 v[8:9], v[2:3], v[136:137]
	v_pk_mul_f32 v[2:3], v[0:1], v[144:145]
	v_cvt_pk_bf16_f32 v0, v4, v5
	v_lshl_add_u64 v[4:5], v[114:115], 0, v[12:13]
	v_lshl_add_u64 v[4:5], v[4:5], 0, v[14:15]
	v_lshl_add_u64 v[4:5], v[4:5], 0, v[80:81]
	v_cvt_pk_bf16_f32 v1, v6, v7
	v_cvt_pk_bf16_f32 v2, v2, v3
	v_cvt_pk_bf16_f32 v3, v8, v9
	global_store_dwordx4 v[4:5], v[0:3], off
	s_cbranch_scc0 .LBB0_650
	s_waitcnt vmcnt(0)
	s_cmpk_gt_u32 s19, 0xff
	s_mov_b32 s86, 0x7f800000
	s_brev_b32 s82, 1
	s_cbranch_scc1 .LBB0_632
	s_barrier
	s_branch .LBB0_632
